# previous plus XCD-leader path of the grid barrier: L1 invalidate issued before the cross-XCD wait; kept after it only for the leader that releases
# baseline (speedup 1.0000x reference)
; __device__ __forceinline__ unsigned xb_add(unsigned* p, unsigned v) { return __hip_atomic_fetch_add(p, v, __ATOMIC_RELAXED, __HIP_MEMORY_SCOPE_AGENT); }
; __device__ __forceinline__ void xcd_barrier(const XcdBarrier& b, int tid_in) {
;     ...
;             __builtin_amdgcn_fence(__ATOMIC_ACQUIRE, "agent");
;             xb_add(&bar[XB_XGEN(b.x)], 1u);
;             asm volatile("s_waitcnt vmcnt(0)" ::: "memory");
.LBB0_7:
	s_mov_b64 s[10:11], exec
	s_or_b64 exec, exec, s[0:1]
	v_mov_b32_e32 v0, s26
	v_add_co_u32_e32 v0, vcc, 0x2000, v0
	v_mov_b32_e32 v1, s25
	s_nop 0
	v_addc_co_u32_e32 v1, vcc, 0, v1, vcc
	s_waitcnt vmcnt(0) lgkmcnt(0)
	s_cmp_eq_u64 s[10:11], 0
	s_cbranch_scc1 .Lldr_noinv
	buffer_inv sc1
.Lldr_noinv:
	flat_atomic_add v[0:1], v221 offset:1024
	s_waitcnt vmcnt(0)

; __device__ __forceinline__ unsigned xb_ld(unsigned* p)              { return __hip_atomic_load(p, __ATOMIC_RELAXED, __HIP_MEMORY_SCOPE_AGENT); }
; __device__ __forceinline__ unsigned xb_add(unsigned* p, unsigned v) { return __hip_atomic_fetch_add(p, v, __ATOMIC_RELAXED, __HIP_MEMORY_SCOPE_AGENT); }
; #define XB_SPIN(cond, bar) do { unsigned _sp = 0; while (cond) { __builtin_amdgcn_s_sleep(1); \
;     if ((++_sp & 255u) == 0u) { if (xb_ld(&(bar)[XB_TMO])) break; if (_sp > XB_SPIN_CAP) { atomicAdd(&(bar)[XB_TMO], 1u); break; } } } } while (0)
; __device__ __forceinline__ void xcd_barrier(const XcdBarrier& b, int tid_in) {
;     ...
;             __builtin_amdgcn_fence(__ATOMIC_RELEASE, "agent");
;             asm volatile("s_waitcnt vmcnt(0)" ::: "memory");
;             const unsigned og = xb_add(&bar[XB_TOP], 1u);
;             const unsigned tg = og / nx;
;             if (og + 1u == (tg + 1u) * nx) xb_add(&bar[XB_TOPGEN], 1u);
;             else XB_SPIN(xb_ld(&bar[XB_TOPGEN]) == tg, bar);
.LBB0_552:
	s_andn2_saveexec_b64 s[4:5], s[4:5]
	s_cbranch_execz .LBB0_8
	v_mov_b32_e32 v1, s0
	v_add_co_u32_e32 v2, vcc, 0x3000, v1
	v_mov_b32_e32 v1, s1
	buffer_wbl2 sc1
	s_waitcnt vmcnt(0)
	v_addc_co_u32_e32 v3, vcc, 0, v1, vcc
	flat_atomic_add v1, v[2:3], v221 offset:1024 sc0
	v_cvt_f32_u32_e32 v2, v0
	v_sub_u32_e32 v3, 0, v0
	s_mov_b64 s[8:9], -1
	v_rcp_iflag_f32_e32 v2, v2
	s_nop 0
	v_mul_f32_e32 v2, 0x4f7ffffe, v2
	v_cvt_u32_f32_e32 v2, v2
	v_mul_lo_u32 v3, v3, v2
	v_mul_hi_u32 v3, v2, v3
	v_add_u32_e32 v2, v2, v3
	s_waitcnt vmcnt(0) lgkmcnt(0)
	v_mul_hi_u32 v2, v1, v2
	v_mul_lo_u32 v3, v2, v0
	v_sub_u32_e32 v3, v1, v3
	v_cmp_ge_u32_e32 vcc, v3, v0
	v_add_u32_e32 v4, 1, v2
	s_nop 0
	v_cndmask_b32_e32 v2, v2, v4, vcc
	v_sub_u32_e32 v4, v3, v0
	v_cndmask_b32_e32 v3, v3, v4, vcc
	v_cmp_ge_u32_e32 vcc, v3, v0
	v_add_u32_e32 v3, 1, v2
	s_nop 0
	v_cndmask_b32_e32 v2, v2, v3, vcc
	v_add_u32_e32 v3, 1, v1
	v_mad_u64_u32 v[0:1], s[4:5], v0, v2, v[0:1]
	s_add_u32 s4, s0, 0x3500
	s_addc_u32 s5, s1, 0
	v_cmp_ne_u32_e32 vcc, v3, v0
	v_mov_b64_e32 v[0:1], s[4:5]
	s_and_saveexec_b64 s[6:7], vcc
	s_cbranch_execz .LBB0_565
	buffer_inv sc1
	v_mov_b64_e32 v[0:1], s[4:5]
	flat_load_dword v0, v[0:1] sc1
	s_mov_b64 s[12:13], 0
	s_waitcnt vmcnt(0) lgkmcnt(0)
	v_cmp_eq_u32_e32 vcc, v0, v2
	s_and_saveexec_b64 s[10:11], vcc
	s_cbranch_execz .LBB0_564
	s_add_u32 s8, s0, 0x200
	s_addc_u32 s9, s1, 0
	s_mov_b32 s22, 1
	s_mov_b64 s[0:1], 0
	s_branch .LBB0_557
